# baseline (speedup 1.0000x reference)
; DEVI void phase_attn(const Params& p, char* shm) {
;   int tid = threadIdx.x;
;   asm volatile("" : "+v"(tid));
;   const int wid = tid >> 6, lane = tid & 63, r32 = lane & 31, hi = lane >> 5;
;   const u16* qb = (const u16*)(p.ws + OFF_QB); const u16* kb = (const u16*)(p.ws + OFF_KB); const u16* vt = (const u16*)(p.ws + OFF_VT);
;   const u16* gb = (const u16*)(p.ws + OFF_GB); u16* og = (u16*)(p.ws + OFF_OG); const float* c2 = (const float*)(p.ws + OFF_LF);
;   char* Ks = shm; char* Vs = shm + 32768; char* Kx = shm + 65536;
;   float* al_l = (float*)(shm + 73728) + wid * 32; float* li_l = (float*)(shm + 74752) + wid * 32; int* jlo_s = (int*)(shm + 75776);
;   const float QKB = gain_bound(p);
;   const float PRUNE = -(2.f * QKB + 30.f);
;   constexpr float THR2 = 11.5f;
;   const int nitems = 2048 + 16;
;   for (int item = blockIdx.x; item < nitems; item += gridDim.x) {
.LBB0_265:
	s_or_b64 exec, exec, s[4:5]
	v_readfirstlane_b32 s98, v220
	s_nop 3
	s_lshr_b32 s98, s98, 6
	s_cmp_ge_u32 s98, 4
	s_cbranch_scc0 .Lprio_attn_done
	s_setprio 1
.Lprio_attn_done:
	v_mov_b32_e32 v178, v220
	s_mov_b64 s[4:5], 0
	v_mov_b32_e32 v2, 0
	v_mov_b32_e32 v0, 0
	v_mov_b32_e32 v1, 0
	s_barrier

; DEVI void phase_attn(const Params& p, char* shm) {
;     ...
;     __syncthreads();
;   }
; }
; __global__ void __launch_bounds__(NTHR) fwd_megakernel(Params p) {
;     ...
;   grid.sync();
.LBB0_356:
	s_setprio 0
	s_waitcnt vmcnt(0)
	s_barrier
	s_and_saveexec_b64 s[4:5], s[0:1]
	s_cbranch_execz .LBB0_366
	buffer_wbl2 sc1
	s_waitcnt vmcnt(0)
	s_load_dword s8, s[76:77], 0x0
	s_add_u32 s6, s74, 0x7620900
	s_addc_u32 s7, s75, 0
	v_mov_b32_e32 v2, 0x100
	v_mov_b32_e32 v3, 1
	global_atomic_add v3, v2, v3, s[6:7] sc0
	s_waitcnt lgkmcnt(0)
	s_mul_i32 s8, s8, 3
	s_waitcnt vmcnt(0)
	v_readfirstlane_b32 s9, v3
	s_nop 0
	s_add_u32 s9, s9, 1
	s_cmp_lg_u32 s9, s8
	s_cbranch_scc1 .Lxb_wait_3
	v_mov_b32_e32 v2, 0x1000
	v_mov_b32_e32 v3, 3
	s_mov_b32 s10, 32

; DEVI void phase_hgrn2(const Params& p, char* shm) {
;   int tid = threadIdx.x;
;   asm volatile("" : "+v"(tid));
;   const int wid = tid >> 6, lane = tid & 63, fr = lane & 15, fq = lane >> 4;
;   const u16* qt = (const u16*)(p.ws + OFF_QT); const u16* kt = (const u16*)(p.ws + OFF_KT);
;   const u16* kht = (const u16*)(p.ws + OFF_KHT); const u16* vtt = (const u16*)(p.ws + OFF_VTT); const float* dec = (const float*)(p.ws + OFF_DEC);
;   const u16* sg = (const u16*)(p.ws + OFF_SG); u16* qo = (u16*)(p.ws + OFF_QT);
;   const float* sloc = (const float*)(p.ws + OFF_SLOC); const float* dseg = (const float*)(p.ws + OFF_DSEG);
;   u16* As = (u16*)shm;
;   u16* ST = (u16*)(shm + 9216);
;   float* part = (float*)(shm + 9216 + 34816);
;   const int tb = wid & 3, wh = wid >> 2;
;   for (int item = blockIdx.x; item < 256; item += gridDim.x) {
;     const int seg = item >> 5, h = item & 7, b = (item >> 3) & 3;
;     f32x4 S[8];
; #pragma unroll
;     for (int n = 0; n < 8; ++n) S[n] = f32x4{0.f, 0.f, 0.f, 0.f};
;     {
;       f32x4 F = {1.f, 1.f, 1.f, 1.f};
;     ...
;         const bool metac = cb < 0;
;         const int rowc = metac ? MREAL : b * SEQ + cb * 64;
;         bf16x8 kf[2], vf[8][2];
;         if (metac) hg_load_kv<true>(kf, vf, kht, vtt, h, rowc, wid, fr, fq);
;         else hg_load_kv<false>(kf, vf, kht, vtt, h, rowc, wid, fr, fq);
;         const f32x4 d4 = *reinterpret_cast<const f32x4*>(dec + (size_t)(rowc >> 6) * 1024 + h * 128 + wid * 16 + fq * 4);
; #pragma unroll
;         for (int n = 0; n < 8; ++n) {
;           f32x4 T = {0.f, 0.f, 0.f, 0.f};
;           T = __builtin_amdgcn_mfma_f32_16x16x32_bf16(kf[0], vf[n][0], T, 0, 0, 0);
;           T = __builtin_amdgcn_mfma_f32_16x16x32_bf16(kf[1], vf[n][1], T, 0, 0, 0);
; #pragma unroll
;           for (int j = 0; j < 4; ++j) S[n][j] += F[j] * T[j];
;         }
;         F = F * d4;
;         float mx = fmaxf(fmaxf(F[0], F[1]), fmaxf(F[2], F[3]));
;         mx = wave_max(mx);
;         if (mx < 9.0949470177e-13f) break;
;       }
;     }
;     float gn[4];
; #pragma unroll
;     for (int nn = 0; nn < 4; ++nn) gn[nn] = p.hg_gn[(wh * 4 + nn) * 16 + fr];
;     bf16x8 qa[4], kb[2][4];
;     ...
;     HG_LOAD_QK(b * SEQ + (seg * 16) * 64);
;     for (int c = 0; c < 16; ++c) {
.LBB0_519:
	s_or_b64 exec, exec, s[8:9]
	v_readfirstlane_b32 s98, v220
	s_nop 3
	s_lshr_b32 s98, s98, 6
	s_cmp_ge_u32 s98, 4
	s_cbranch_scc0 .Lprio_hg_done
	s_setprio 1
.Lprio_hg_done:
	v_mov_b32_e32 v1, v220
	s_cmpk_gt_i32 s2, 0xff
	s_barrier
	s_cbranch_scc1 .LBB0_560
	v_ashrrev_i32_e32 v7, 6, v1
	v_lshlrev_b32_e32 v4, 4, v7
	v_and_b32_e32 v223, 15, v1
	v_bfe_u32 v12, v1, 4, 2
	v_mov_b32_e32 v0, 0
	v_ashrrev_i32_e32 v5, 31, v4
	v_and_b32_e32 v10, 3, v7
	v_or_b32_e32 v224, v4, v223
	v_lshlrev_b32_e32 v8, 4, v12
	v_mov_b32_e32 v9, v0
	v_lshl_add_u64 v[4:5], v[4:5], 2, s[66:67]
	v_lshl_add_u64 v[184:185], v[4:5], 0, v[8:9]
	v_lshlrev_b32_e32 v4, 4, v10
	v_or_b32_e32 v225, v4, v223
	v_lshl_or_b32 v227, v12, 2, v4
	v_lshlrev_b32_e32 v4, 1, v223
	v_mov_b32_e32 v5, v0
	v_lshl_add_u64 v[192:193], s[20:21], 0, v[4:5]
	v_mbcnt_lo_u32_b32 v4, -1, 0
	v_mbcnt_hi_u32_b32 v4, -1, v4
	v_lshl_add_u64 v[176:177], s[58:59], 0, v[8:9]
	v_lshl_add_u64 v[178:179], s[74:75], 0, v[8:9]
	v_lshl_add_u64 v[190:191], s[60:61], 0, v[8:9]
	v_lshl_add_u64 v[194:195], s[46:47], 0, v[8:9]
	v_and_b32_e32 v9, 64, v4
	v_xor_b32_e32 v5, 1, v4
	v_add_u32_e32 v9, 64, v9
	v_cmp_lt_i32_e32 vcc, v5, v9
	s_mov_b64 s[8:9], 0x137e0500
	v_lshl_add_u64 v[180:181], v[178:179], 0, s[8:9]
	v_cndmask_b32_e32 v5, v4, v5, vcc
	v_lshlrev_b32_e32 v229, 2, v5
	v_xor_b32_e32 v5, 2, v4
	v_cmp_lt_i32_e32 vcc, v5, v9
	s_mov_b64 s[8:9], 0x137f0500
	v_lshl_add_u64 v[182:183], v[178:179], 0, s[8:9]
	v_cndmask_b32_e32 v5, v4, v5, vcc
	v_lshlrev_b32_e32 v230, 2, v5
	v_xor_b32_e32 v5, 4, v4
	v_cmp_lt_i32_e32 vcc, v5, v9
	s_movk_i32 s8, 0x90
	v_mad_u32_u24 v228, v225, s8, v8
	v_cndmask_b32_e32 v5, v4, v5, vcc
	s_movk_i32 s8, 0x100
	v_lshlrev_b32_e32 v231, 2, v5
	v_xor_b32_e32 v5, 8, v4
	v_ashrrev_i32_e32 v11, 8, v1
	v_cmp_gt_u32_e64 s[8:9], s8, v1
	v_cmp_lt_i32_e32 vcc, v5, v9
	v_and_b32_e32 v234, 0xffffff00, v1
	v_xor_b32_e32 v1, 16, v4
	v_cndmask_b32_e32 v5, v4, v5, vcc
	v_cmp_lt_i32_e32 vcc, v1, v9
	v_lshlrev_b32_e32 v186, 6, v11
	v_lshl_or_b32 v226, v11, 5, v223
	v_cndmask_b32_e32 v1, v4, v1, vcc
	v_lshlrev_b32_e32 v235, 2, v1
	v_xor_b32_e32 v1, 32, v4
	v_cmp_lt_i32_e32 vcc, v1, v9
	v_lshlrev_b32_e32 v6, 3, v12
	v_or_b32_e32 v188, v186, v223
	v_lshlrev_b32_e32 v232, 2, v5
	v_cndmask_b32_e32 v1, v4, v1, vcc
	v_or_b32_e32 v237, 1, v227
	v_or_b32_e32 v238, 2, v227
	v_or_b32_e32 v239, 3, v227
	v_or_b32_e32 v5, 16, v226
	s_movk_i32 s34, 0x110
	v_mov_b32_e32 v2, s64
	v_mov_b32_e32 v3, s65
	v_lshlrev_b32_e32 v11, 1, v11
	v_lshl_or_b32 v7, v7, 5, v6
	v_lshlrev_b32_e32 v236, 2, v1
	v_ashrrev_i32_e32 v189, 31, v188
	v_lshlrev_b32_e32 v1, 1, v226
	v_mul_u32_u24_e32 v4, 0x90, v227
	v_cmp_gt_i32_e64 s[24:25], v5, v227
	v_cmp_gt_i32_e64 s[26:27], v5, v237
	v_cmp_gt_i32_e64 s[28:29], v5, v238
	v_cmp_gt_i32_e64 s[30:31], v5, v239
	v_mul_u32_u24_e32 v5, 0x110, v223
	v_mul_lo_u32 v9, v188, s34
	v_lshlrev_b32_e32 v200, 1, v6
	v_cmp_gt_u32_e64 s[36:37], 2, v12
	s_mov_b32 s51, 0
	v_cmp_eq_u32_e64 s[10:11], 0, v223
	v_lshl_or_b32 v233, v10, 6, v8
	v_cmp_le_i32_e64 s[12:13], v11, v10
	v_cmp_gt_i32_e64 s[14:15], v226, v227
	v_cmp_gt_i32_e64 s[16:17], v226, v237
	v_cmp_gt_i32_e64 s[18:19], v226, v238
	v_cmp_gt_i32_e64 s[20:21], v226, v239
	v_cmp_ge_i32_e64 s[22:23], v11, v10
	v_ashrrev_i32_e32 v187, 31, v186
	v_lshlrev_b32_e32 v240, 2, v227
	v_lshl_add_u64 v[196:197], v[188:189], 2, v[2:3]
	s_lshl_b32 s45, s2, 10
	s_lshl_b32 s80, s3, 10
	v_or_b32_e32 v241, 64, v225
	s_lshl_b32 s81, s2, 7
	s_lshl_b32 s82, s3, 7
	s_mov_b32 s83, 0x10080
	v_mov_b64_e32 v[198:199], s[58:59]
	v_mov_b32_e32 v202, v200
	v_mov_b32_e32 v203, v0
	s_mov_b64 s[52:53], 0x10000
	s_mov_b64 s[54:55], 0x100800
	s_mov_b64 s[56:57], 0x201000
	s_mov_b64 s[58:59], 0x301800
	s_mov_b64 s[60:61], 0x402000
	s_mov_b64 s[62:63], 0x502800
	s_mov_b64 s[64:65], 0x603000
	s_mov_b64 s[66:67], 0x703800
	s_mov_b32 s84, 0x2b800000
	s_mov_b32 s85, 0xf760000
	s_mov_b32 s86, 0x137e0000
	s_mov_b32 s87, 0x138e0000
	s_mov_b32 s88, 0x139e1000
	s_mov_b32 s89, 0x13ae1000
	s_mov_b32 s90, 0x13be2000
	s_mov_b32 s91, 0x13ce2000
	v_mov_b32_e32 v242, 0x358637bd
	v_add_u32_e32 v243, v1, v4
	v_add_u32_e32 v244, v7, v5
	v_add_u32_e32 v245, v8, v9
	s_mov_b32 s92, s2
	s_branch .LBB0_522

; DEVI void phase_hgrn2(const Params& p, char* shm) {
;     ...
;     __syncthreads();
;   }
; }
; __global__ void __launch_bounds__(NTHR) fwd_megakernel(Params p) {
;     ...
;   grid.sync();
.LBB0_560:
	s_setprio 0
	s_waitcnt vmcnt(0)
	s_barrier
	s_and_saveexec_b64 s[8:9], s[0:1]
	s_cbranch_execz .LBB0_570
	buffer_wbl2 sc1
	s_waitcnt vmcnt(0)
	s_load_dword s12, s[76:77], 0x0
	s_add_u32 s10, s74, 0x7620900
	s_addc_u32 s11, s75, 0
	v_mov_b32_e32 v2, 0x100
	v_mov_b32_e32 v3, 1
	global_atomic_add v3, v2, v3, s[10:11] sc0
	s_waitcnt lgkmcnt(0)
	s_mul_i32 s12, s12, 8
	s_waitcnt vmcnt(0)
	v_readfirstlane_b32 s13, v3
	s_nop 0
	s_add_u32 s13, s13, 1
	s_cmp_lg_u32 s13, s12
	s_cbranch_scc1 .Lxb_wait_8
	v_mov_b32_e32 v2, 0x1000
	v_mov_b32_e32 v3, 8
	s_mov_b32 s14, 32
